# v102: v99 plus the static priority raise for waves 0-3 during the mLSTM output pass (reset at the common post-phase point)
# speedup vs baseline: 1.0015x; 1.0015x over previous
.LBB0_168:
	s_cmpk_lt_i32 s12, 0x180
	v_readlane_b32 s2, v254, 5
	s_cselect_b64 s[0:1], -1, 0
	v_readlane_b32 s3, v254, 6
	s_or_b64 s[0:1], s[2:3], s[0:1]
	s_andn2_b64 vcc, exec, s[0:1]
	s_cbranch_vccnz .LBB0_274
	v_writelane_b32 v255, s80, 29
	v_writelane_b32 v255, s67, 26
	v_readlane_b32 s6, v254, 63
	v_readlane_b32 s0, v255, 5
	v_readlane_b32 s2, v255, 7
	v_readlane_b32 s3, v255, 8
	s_add_u32 s74, s2, 0x200000
	s_addc_u32 s75, s3, 0
	s_add_u32 s0, s2, 0xd000000
	v_readlane_b32 s1, v255, 6
	v_writelane_b32 v255, s0, 32
	s_addc_u32 s0, s3, 0
	v_writelane_b32 v255, s0, 34
	s_add_u32 s0, s2, 0xe800000
	v_writelane_b32 v255, s0, 36
	s_addc_u32 s0, s3, 0
	v_writelane_b32 v255, s0, 37
	s_add_u32 s0, s2, 0x11800000
	v_writelane_b32 v255, s0, 38
	s_addc_u32 s0, s3, 0
	v_writelane_b32 v255, s0, 39
	s_add_u32 s0, s2, 0x13000000
	s_addc_u32 s1, s3, 0
	v_writelane_b32 v255, s0, 40
	s_add_u32 s80, s2, 0x1800000
	s_addc_u32 s81, s3, 0
	v_writelane_b32 v255, s1, 41
	s_lshl_b32 s0, s6, 11
	s_add_i32 s0, s0, 0
	s_add_i32 s0, s0, 0x21800
	v_writelane_b32 v255, s0, 42
	s_lshl_b32 s0, s6, 4
	s_add_u32 s1, s2, 0x14800000
	s_addc_u32 s46, s3, 0
	v_readlane_b32 vcc_lo, v254, 63
	s_cmp_lt_u32 vcc_lo, 4
	s_cbranch_scc0 .Lprio2_done
	s_setprio 1
.Lprio2_done:
	s_cmp_lt_i32 s6, 1
	s_cselect_b64 s[2:3], -1, 0
	v_writelane_b32 v255, s2, 27
	s_cmp_gt_i32 s6, -1
	v_mbcnt_lo_u32_b32 v0, -1, v0
	v_writelane_b32 v255, s3, 28
	s_cselect_b64 s[2:3], -1, 0
	v_writelane_b32 v255, s2, 43
	s_cmp_lt_i32 s6, 2
	v_mbcnt_hi_u32_b32 v164, -1, v0
	v_writelane_b32 v255, s3, 44
	s_cselect_b64 s[2:3], -1, 0
	v_writelane_b32 v255, s2, 45
	s_cmp_gt_i32 s6, 0
	v_lshl_add_u32 v165, s6, 6, v164
	v_writelane_b32 v255, s3, 46
	s_cselect_b64 s[2:3], -1, 0
	v_writelane_b32 v255, s2, 47
	s_cmp_lt_i32 s6, 3
	s_mov_b32 s8, 0
	v_writelane_b32 v255, s3, 48
	s_cselect_b64 s[2:3], -1, 0
	v_writelane_b32 v255, s2, 49
	s_cmp_gt_i32 s6, 1
	s_nop 0
	v_writelane_b32 v255, s3, 50
	s_cselect_b64 s[2:3], -1, 0
	v_writelane_b32 v255, s2, 51
	s_cmp_lt_i32 s6, 4
	s_nop 0
	v_writelane_b32 v255, s3, 52
	s_cselect_b64 s[2:3], -1, 0
	v_writelane_b32 v255, s2, 53
	s_cmp_gt_i32 s6, 2
	s_nop 0
	v_writelane_b32 v255, s3, 54
	s_cselect_b64 s[2:3], -1, 0
	s_cmp_lt_i32 s6, 5
	s_cselect_b64 s[76:77], -1, 0
	s_cmp_gt_i32 s6, 3
	s_cselect_b64 s[92:93], -1, 0
	s_cmp_lt_i32 s6, 6
	s_cselect_b64 s[66:67], -1, 0
	s_cmp_gt_i32 s6, 4
	s_cselect_b64 s[84:85], -1, 0
	s_cmp_lt_i32 s6, 7
	s_cselect_b64 s[40:41], -1, 0
	s_cmp_gt_i32 s6, 5
	s_cselect_b64 s[50:51], -1, 0
	s_cmp_lt_i32 s6, 8
	v_writelane_b32 v255, s2, 57
	s_cselect_b64 s[60:61], -1, 0
	s_cmp_gt_i32 s6, 6
	v_writelane_b32 v255, s3, 58
	s_cselect_b64 s[70:71], -1, 0
	s_branch .LBB0_171

.LBB0_893:
	s_setprio 0
	s_cmpk_lt_i32 s67, 192
	s_cbranch_scc1 .Ladh_skip
	v_readlane_b32 s1, v254, 61
	s_mov_b32 s20, -1
	s_mov_b32 s2, 0
	s_cmp_eq_u32 s1, 3
	s_cselect_b32 s20, 1, s20
	s_cselect_b32 s2, 0, s2
	s_cmp_eq_u32 s1, 12
	s_cselect_b32 s20, 2, s20
	s_cselect_b32 s2, 0, s2
	s_cmp_eq_u32 s1, 19
	s_cselect_b32 s20, 3, s20
	s_cselect_b32 s2, 0, s2
	s_cmp_eq_u32 s1, 8
	s_cselect_b32 s20, 0, s20
	s_cselect_b32 s2, 256, s2
	s_cmp_lt_i32 s20, 0
	s_cbranch_scc1 .Ladh_skip
	v_readlane_b32 s0, v254, 63
	s_sub_i32 s3, s67, 192
	s_add_i32 s3, s3, s2
	s_cmpk_ge_i32 s3, 0x120
	s_cbranch_scc1 .Ladh_skip
	s_load_dwordx4 s[8:11], s[60:61], 0x38
	s_load_dwordx4 s[12:15], s[60:61], 0x48
	v_mbcnt_lo_u32_b32 v0, -1, 0
	v_mbcnt_hi_u32_b32 v0, -1, v0
	s_lshl_b32 s16, s0, 14
	s_lshl_b32 s1, s0, 9
	v_lshl_add_u32 v18, v0, 2, s1
	v_lshl_add_u32 v19, v0, 4, s16
	s_waitcnt lgkmcnt(0)
	s_add_u32 s6, s8, 0x1000
	s_addc_u32 s7, s9, 0
	global_load_dword v26, v18, s[10:11]
	global_load_dword v27, v18, s[10:11] offset:256
	global_load_dword v28, v18, s[8:9]
	global_load_dword v29, v18, s[8:9] offset:256
	global_load_dword v30, v18, s[6:7]
	global_load_dword v31, v18, s[6:7] offset:256
	s_waitcnt vmcnt(0)
	v_mul_f32_e32 v74, 0xbfb8aa3b, v26
	v_mul_f32_e32 v75, 0xbfb8aa3b, v27
	v_mul_f32_e32 v76, 0xbfb8aa3b, v28
	v_mul_f32_e32 v77, 0xbfb8aa3b, v29
	v_mul_f32_e32 v78, 0xbfb8aa3b, v30
	v_mul_f32_e32 v79, 0xbfb8aa3b, v31
	v_exp_f32_e32 v74, v74
	v_exp_f32_e32 v75, v75
	v_exp_f32_e32 v76, v76
	v_exp_f32_e32 v77, v77
	v_exp_f32_e32 v78, v78
	v_exp_f32_e32 v79, v79
	v_add_f32_e32 v74, 1.0, v74
	v_add_f32_e32 v75, 1.0, v75
	v_add_f32_e32 v76, 1.0, v76
	v_add_f32_e32 v77, 1.0, v77
	v_add_f32_e32 v78, 1.0, v78
	v_add_f32_e32 v79, 1.0, v79
	v_rcp_f32_e32 v74, v74
	v_rcp_f32_e32 v75, v75
	v_rcp_f32_e32 v76, v76
	v_rcp_f32_e32 v77, v77
	v_rcp_f32_e32 v78, v78
	v_rcp_f32_e32 v79, v79
	v_mul_f32_e32 v26, v26, v74
	v_mul_f32_e32 v27, v27, v75
	v_mul_f32_e32 v28, v28, v76
	v_mul_f32_e32 v29, v29, v77
	v_mul_f32_e32 v30, v30, v78
	v_mul_f32_e32 v31, v31, v79
	v_mov_b32_e32 v90, v26
	v_mov_b32_e32 v91, v28
	v_mov_b32_e32 v92, v30
	v_mov_b32_e32 v93, 0
	v_mov_b32_e32 v94, v27
	v_mov_b32_e32 v95, v29
	v_mov_b32_e32 v96, v31
	v_mov_b32_e32 v97, 0
	ds_write_b128 v19, v[90:93]
	ds_write_b128 v19, v[94:97] offset:1024
	v_lshrrev_b32_e32 v20, 3, v0
	v_and_b32_e32 v21, 7, v0
	v_mul_u32_u24_e32 v22, 0x9000, v20
	v_lshl_add_u32 v22, v21, 4, v22
	s_mul_i32 s17, s0, 0x480000
	s_mul_i32 s1, s20, 0x2400000
	s_add_u32 s17, s17, s1
	s_add_u32 s12, s12, s17
	s_addc_u32 s13, s13, 0
	s_mul_i32 s1, s20, 0x9000
	s_add_u32 s14, s14, s1
	s_addc_u32 s15, s15, 0
	v_lshl_add_u32 v23, v20, 4, s16
	s_mul_i32 s17, s0, 0x180
	s_add_i32 s17, s17, 131072
	v_readlane_b32 s8, v255, 7
	v_readlane_b32 s9, v255, 8
	s_mul_i32 s1, s20, 0x1b000
	s_add_i32 s1, s1, 0x100000
	s_add_u32 s8, s8, s1
	s_addc_u32 s9, s9, 0
	s_mov_b32 s18, s3
	s_waitcnt lgkmcnt(0)
	v_lshl_add_u32 v94, v21, 4, s17
	s_mov_b32 s17, 131072
	v_lshl_add_u32 v95, v0, 2, s17
	v_lshlrev_b32_e32 v96, 2, v0
